# v29 + PV first V reads issued before the exp section (sel/window interior), sel non-interior QK fragments up front
# baseline (speedup 1.0000x reference)
.LBB0_871:
	v_add_u32_e32 v237, s74, v182
	ds_read_b64_tr_b16 v[238:239], v237 offset:18432
	ds_read_b64_tr_b16 v[240:241], v237 offset:19200
	ds_read_b64_tr_b16 v[242:243], v237 offset:18496
	ds_read_b64_tr_b16 v[244:245], v237 offset:19264
	ds_read_b64_tr_b16 v[246:247], v237 offset:21504
	ds_read_b64_tr_b16 v[248:249], v237 offset:22272
	ds_read_b64_tr_b16 v[250:251], v237 offset:21568
	ds_read_b64_tr_b16 v[252:253], v237 offset:22336
	v_mul_f32_e64 v42, -v118, v110
	v_sub_f32_e32 v42, v0, v42
	v_sub_f32_e32 v43, v109, v42
	v_exp_f32_e32 v43, v43
	v_sub_f32_e32 v45, v108, v42
	v_exp_f32_e32 v45, v45
	v_sub_f32_e32 v46, v107, v42
	v_exp_f32_e32 v46, v46
	v_sub_f32_e32 v47, v106, v42
	v_exp_f32_e32 v47, v47
	v_sub_f32_e32 v48, v105, v42
	v_add_f32_e32 v44, 0, v43
	v_exp_f32_e32 v48, v48
	v_sub_f32_e32 v49, v104, v42
	v_add_f32_e32 v44, v45, v44
	v_exp_f32_e32 v49, v49
	v_sub_f32_e32 v62, v103, v42
	v_add_f32_e32 v44, v46, v44
	v_exp_f32_e32 v62, v62
	v_sub_f32_e32 v63, v102, v42
	v_add_f32_e32 v44, v47, v44
	v_exp_f32_e32 v63, v63
	v_sub_f32_e32 v64, v101, v42
	v_add_f32_e32 v44, v48, v44
	v_exp_f32_e32 v64, v64
	v_sub_f32_e32 v65, v100, v42
	v_add_f32_e32 v44, v49, v44
	v_exp_f32_e32 v65, v65
	v_sub_f32_e32 v99, v99, v42
	v_add_f32_e32 v44, v62, v44
	v_exp_f32_e32 v99, v99
	v_sub_f32_e32 v98, v98, v42
	v_add_f32_e32 v44, v63, v44
	v_exp_f32_e32 v98, v98
	v_sub_f32_e32 v61, v61, v42
	v_add_f32_e32 v44, v64, v44
	v_exp_f32_e32 v61, v61
	v_sub_f32_e32 v60, v60, v42
	v_add_f32_e32 v44, v65, v44
	v_exp_f32_e32 v60, v60
	v_sub_f32_e32 v59, v59, v42
	v_add_f32_e32 v44, v99, v44
	v_exp_f32_e32 v59, v59
	v_sub_f32_e32 v58, v58, v42
	v_add_f32_e32 v44, v98, v44
	v_exp_f32_e32 v58, v58
	v_sub_f32_e32 v57, v57, v42
	v_add_f32_e32 v44, v61, v44
	v_exp_f32_e32 v57, v57
	v_sub_f32_e32 v56, v56, v42
	v_add_f32_e32 v44, v60, v44
	v_exp_f32_e32 v56, v56
	v_sub_f32_e32 v55, v55, v42
	v_add_f32_e32 v44, v59, v44
	v_exp_f32_e32 v55, v55
	v_sub_f32_e32 v54, v54, v42
	v_add_f32_e32 v44, v58, v44
	v_exp_f32_e32 v54, v54
	v_sub_f32_e32 v53, v53, v42
	v_add_f32_e32 v44, v57, v44
	v_exp_f32_e32 v53, v53
	v_sub_f32_e32 v52, v52, v42
	v_add_f32_e32 v44, v56, v44
	v_exp_f32_e32 v52, v52
	v_sub_f32_e32 v51, v51, v42
	v_add_f32_e32 v44, v55, v44
	v_exp_f32_e32 v51, v51
	v_sub_f32_e32 v50, v50, v42
	v_add_f32_e32 v44, v54, v44
	v_exp_f32_e32 v50, v50
	v_sub_f32_e32 v41, v41, v42
	v_add_f32_e32 v44, v53, v44
	v_exp_f32_e32 v100, v41
	v_add_f32_e32 v44, v52, v44
	v_add_f32_e32 v44, v51, v44
	v_add_f32_e32 v44, v50, v44
	v_sub_f32_e32 v40, v40, v42
	v_add_f32_e32 v41, v100, v44
	v_exp_f32_e32 v44, v40
	v_sub_f32_e32 v39, v39, v42
	v_exp_f32_e32 v101, v39
	v_sub_f32_e32 v38, v38, v42
	v_exp_f32_e32 v102, v38
	v_sub_f32_e32 v37, v37, v42
	v_exp_f32_e32 v103, v37
	v_sub_f32_e32 v36, v36, v42
	v_add_f32_e32 v40, v44, v41
	v_exp_f32_e32 v104, v36
	v_sub_f32_e32 v35, v35, v42
	v_add_f32_e32 v39, v101, v40
	v_exp_f32_e32 v105, v35
	v_sub_f32_e32 v34, v34, v42
	v_add_f32_e32 v38, v102, v39
	v_exp_f32_e32 v42, v34
	v_add_f32_e32 v37, v103, v38
	v_add_f32_e32 v36, v104, v37
	v_add_f32_e32 v35, v105, v36
	v_add_f32_e32 v34, v42, v35
	v_add_f32_e32 v127, v34, v124
	v_cvt_pk_bf16_f32 v34, v43, v45
	v_cvt_pk_bf16_f32 v35, v46, v47
	v_cvt_pk_bf16_f32 v36, v48, v49
	v_cvt_pk_bf16_f32 v37, v62, v63
	s_nop 0
	s_nop 0
	s_waitcnt lgkmcnt(6)
	v_mfma_f32_32x32x16_bf16 v[2:17], v[238:241], v[34:37], v[2:17]
	ds_read_b64_tr_b16 v[238:239], v237 offset:24576
	ds_read_b64_tr_b16 v[240:241], v237 offset:25344
	s_nop 0
	s_waitcnt lgkmcnt(6)
	v_mfma_f32_32x32x16_bf16 v[18:33], v[242:245], v[34:37], v[18:33]
	ds_read_b64_tr_b16 v[242:243], v237 offset:24640
	ds_read_b64_tr_b16 v[244:245], v237 offset:25408
	v_cvt_pk_bf16_f32 v34, v64, v65
	v_cvt_pk_bf16_f32 v35, v99, v98
	v_cvt_pk_bf16_f32 v36, v61, v60
	v_cvt_pk_bf16_f32 v37, v59, v58
	s_nop 0
	s_nop 0
	s_waitcnt lgkmcnt(6)
	v_mfma_f32_32x32x16_bf16 v[2:17], v[246:249], v[34:37], v[2:17]
	ds_read_b64_tr_b16 v[246:247], v237 offset:27648
	ds_read_b64_tr_b16 v[248:249], v237 offset:28416
	s_nop 0
	s_waitcnt lgkmcnt(6)
	v_mfma_f32_32x32x16_bf16 v[18:33], v[250:253], v[34:37], v[18:33]
	ds_read_b64_tr_b16 v[250:251], v237 offset:27712
	ds_read_b64_tr_b16 v[252:253], v237 offset:28480
	v_cvt_pk_bf16_f32 v34, v57, v56
	v_cvt_pk_bf16_f32 v35, v55, v54
	v_cvt_pk_bf16_f32 v36, v53, v52
	v_cvt_pk_bf16_f32 v37, v51, v50
	s_nop 0
	s_nop 0
	s_waitcnt lgkmcnt(6)
	v_mfma_f32_32x32x16_bf16 v[2:17], v[238:241], v[34:37], v[2:17]
	s_nop 0
	s_waitcnt lgkmcnt(4)
	v_mfma_f32_32x32x16_bf16 v[18:33], v[242:245], v[34:37], v[18:33]
	v_cvt_pk_bf16_f32 v34, v100, v44
	v_cvt_pk_bf16_f32 v35, v101, v102
	v_cvt_pk_bf16_f32 v36, v103, v104
	v_cvt_pk_bf16_f32 v37, v105, v42
	s_nop 0
	s_nop 0
	s_waitcnt lgkmcnt(2)
	v_mfma_f32_32x32x16_bf16 v[2:17], v[246:249], v[34:37], v[2:17]
	s_nop 0
	s_waitcnt lgkmcnt(0)
	v_mfma_f32_32x32x16_bf16 v[18:33], v[250:253], v[34:37], v[18:33]

.LBB0_882:
	v_add_u32_e32 v236, s2, v182
	ds_read_b64_tr_b16 v[238:239], v236 offset:18432
	ds_read_b64_tr_b16 v[240:241], v236 offset:19200
	ds_read_b64_tr_b16 v[242:243], v236 offset:18496
	ds_read_b64_tr_b16 v[244:245], v236 offset:19264
	ds_read_b64_tr_b16 v[246:247], v236 offset:21504
	ds_read_b64_tr_b16 v[248:249], v236 offset:22272
	ds_read_b64_tr_b16 v[250:251], v236 offset:21568
	ds_read_b64_tr_b16 v[252:253], v236 offset:22336
	v_mul_f32_e64 v231, -v118, v231
	v_sub_f32_e32 v231, v0, v231
	v_cndmask_b32_e64 v231, v146, v231, s[10:11]
	v_sub_f32_e32 v50, v50, v231
	v_exp_f32_e32 v50, v50
	v_sub_f32_e32 v51, v51, v231
	v_exp_f32_e32 v51, v51
	v_sub_f32_e32 v52, v52, v231
	v_exp_f32_e32 v52, v52
	v_sub_f32_e32 v53, v53, v231
	v_exp_f32_e32 v53, v53
	v_sub_f32_e32 v54, v54, v231
	v_exp_f32_e32 v54, v54
	v_sub_f32_e32 v55, v55, v231
	v_exp_f32_e32 v55, v55
	v_add_f32_e32 v191, v51, v50
	v_sub_f32_e32 v56, v56, v231
	v_exp_f32_e32 v56, v56
	v_add_f32_e32 v191, v52, v191
	v_sub_f32_e32 v57, v57, v231
	v_exp_f32_e32 v57, v57
	v_add_f32_e32 v191, v53, v191
	v_sub_f32_e32 v58, v58, v231
	v_exp_f32_e32 v58, v58
	v_add_f32_e32 v191, v54, v191
	v_sub_f32_e32 v59, v59, v231
	v_exp_f32_e32 v59, v59
	v_add_f32_e32 v191, v55, v191
	v_sub_f32_e32 v60, v60, v231
	v_exp_f32_e32 v60, v60
	v_add_f32_e32 v191, v56, v191
	v_sub_f32_e32 v61, v61, v231
	v_exp_f32_e32 v61, v61
	v_add_f32_e32 v191, v57, v191
	v_sub_f32_e32 v62, v62, v231
	v_exp_f32_e32 v62, v62
	v_add_f32_e32 v191, v58, v191
	v_sub_f32_e32 v63, v63, v231
	v_exp_f32_e32 v63, v63
	v_add_f32_e32 v191, v59, v191
	v_sub_f32_e32 v64, v64, v231
	v_exp_f32_e32 v64, v64
	v_add_f32_e32 v191, v60, v191
	v_sub_f32_e32 v65, v65, v231
	v_exp_f32_e32 v65, v65
	v_add_f32_e32 v191, v61, v191
	v_sub_f32_e32 v34, v34, v231
	v_exp_f32_e32 v34, v34
	v_add_f32_e32 v191, v62, v191
	v_sub_f32_e32 v35, v35, v231
	v_exp_f32_e32 v35, v35
	v_add_f32_e32 v191, v63, v191
	v_sub_f32_e32 v36, v36, v231
	v_exp_f32_e32 v36, v36
	v_add_f32_e32 v191, v64, v191
	v_sub_f32_e32 v37, v37, v231
	v_exp_f32_e32 v37, v37
	v_add_f32_e32 v191, v65, v191
	v_sub_f32_e32 v38, v38, v231
	v_exp_f32_e32 v38, v38
	v_add_f32_e32 v191, v34, v191
	v_sub_f32_e32 v39, v39, v231
	v_exp_f32_e32 v39, v39
	v_add_f32_e32 v191, v35, v191
	v_sub_f32_e32 v40, v40, v231
	v_exp_f32_e32 v40, v40
	v_add_f32_e32 v191, v36, v191
	v_sub_f32_e32 v41, v41, v231
	v_exp_f32_e32 v41, v41
	v_add_f32_e32 v191, v37, v191
	v_sub_f32_e32 v42, v42, v231
	v_exp_f32_e32 v42, v42
	v_add_f32_e32 v191, v38, v191
	v_sub_f32_e32 v43, v43, v231
	v_exp_f32_e32 v43, v43
	v_add_f32_e32 v191, v39, v191
	v_sub_f32_e32 v44, v44, v231
	v_exp_f32_e32 v44, v44
	v_add_f32_e32 v191, v40, v191
	v_sub_f32_e32 v45, v45, v231
	v_exp_f32_e32 v45, v45
	v_add_f32_e32 v191, v41, v191
	v_sub_f32_e32 v46, v46, v231
	v_exp_f32_e32 v46, v46
	v_add_f32_e32 v191, v42, v191
	v_sub_f32_e32 v47, v47, v231
	v_exp_f32_e32 v47, v47
	v_add_f32_e32 v191, v43, v191
	v_sub_f32_e32 v48, v48, v231
	v_exp_f32_e32 v48, v48
	v_add_f32_e32 v191, v44, v191
	v_sub_f32_e32 v49, v49, v231
	v_exp_f32_e32 v49, v49
	v_add_f32_e32 v191, v45, v191
	v_add_f32_e32 v191, v46, v191
	v_add_f32_e32 v191, v47, v191
	v_add_f32_e32 v191, v48, v191
	v_add_f32_e32 v191, v49, v191
	v_add_f32_e32 v191, v191, v229
	v_cvt_pk_bf16_f32 v232, v50, v51
	v_cvt_pk_bf16_f32 v233, v52, v53
	v_cvt_pk_bf16_f32 v234, v54, v55
	v_cvt_pk_bf16_f32 v235, v56, v57
	s_mov_b64 s[18:19], 0
	s_nop 0
	s_waitcnt lgkmcnt(6)
	v_mfma_f32_32x32x16_bf16 v[2:17], v[238:241], v[232:235], v[2:17]
	ds_read_b64_tr_b16 v[238:239], v236 offset:24576
	ds_read_b64_tr_b16 v[240:241], v236 offset:25344
	s_nop 0
	s_waitcnt lgkmcnt(6)
	v_mfma_f32_32x32x16_bf16 v[18:33], v[242:245], v[232:235], v[18:33]
	ds_read_b64_tr_b16 v[242:243], v236 offset:24640
	ds_read_b64_tr_b16 v[244:245], v236 offset:25408
	v_cvt_pk_bf16_f32 v232, v58, v59
	v_cvt_pk_bf16_f32 v233, v60, v61
	v_cvt_pk_bf16_f32 v234, v62, v63
	v_cvt_pk_bf16_f32 v235, v64, v65
	s_nop 0
	s_nop 0
	s_waitcnt lgkmcnt(6)
	v_mfma_f32_32x32x16_bf16 v[2:17], v[246:249], v[232:235], v[2:17]
	ds_read_b64_tr_b16 v[246:247], v236 offset:27648
	ds_read_b64_tr_b16 v[248:249], v236 offset:28416
	s_nop 0
	s_waitcnt lgkmcnt(6)
	v_mfma_f32_32x32x16_bf16 v[18:33], v[250:253], v[232:235], v[18:33]
	ds_read_b64_tr_b16 v[250:251], v236 offset:27712
	ds_read_b64_tr_b16 v[252:253], v236 offset:28480
	v_cvt_pk_bf16_f32 v232, v34, v35
	v_cvt_pk_bf16_f32 v233, v36, v37
	v_cvt_pk_bf16_f32 v234, v38, v39
	v_cvt_pk_bf16_f32 v235, v40, v41
	s_nop 0
	s_nop 0
	s_waitcnt lgkmcnt(6)
	v_mfma_f32_32x32x16_bf16 v[2:17], v[238:241], v[232:235], v[2:17]
	s_nop 0
	s_waitcnt lgkmcnt(4)
	v_mfma_f32_32x32x16_bf16 v[18:33], v[242:245], v[232:235], v[18:33]
	v_cvt_pk_bf16_f32 v232, v42, v43
	v_cvt_pk_bf16_f32 v233, v44, v45
	v_cvt_pk_bf16_f32 v234, v46, v47
	v_cvt_pk_bf16_f32 v235, v48, v49
	s_nop 0
	s_nop 0
	s_waitcnt lgkmcnt(2)
	v_mfma_f32_32x32x16_bf16 v[2:17], v[246:249], v[232:235], v[2:17]
	s_nop 0
	s_waitcnt lgkmcnt(0)
	v_mfma_f32_32x32x16_bf16 v[18:33], v[250:253], v[232:235], v[18:33]
	v_mov_b32_e32 v188, v191
	v_mov_b32_e32 v189, v0
	s_branch .LBB0_888
.LBB0_883:
	ds_read_b128 v[238:241], v192 offset:4608
	ds_read_b128 v[242:245], v192 offset:4640
	ds_read_b128 v[246:249], v192 offset:4672
	ds_read_b128 v[250:253], v192 offset:4704
	s_waitcnt lgkmcnt(7)
	v_mfma_f32_32x32x16_bf16 v[50:65], v[98:101], v[66:69], 0
	s_waitcnt lgkmcnt(6)
	v_mfma_f32_32x32x16_bf16 v[50:65], v[102:105], v[70:73], v[50:65]
	s_waitcnt lgkmcnt(5)
	v_mfma_f32_32x32x16_bf16 v[50:65], v[106:109], v[74:77], v[50:65]
	s_waitcnt lgkmcnt(4)
	v_mfma_f32_32x32x16_bf16 v[50:65], v[110:113], v[78:81], v[50:65]
	s_waitcnt lgkmcnt(3)
	v_mfma_f32_32x32x16_bf16 v[34:49], v[238:241], v[66:69], 0
	s_waitcnt lgkmcnt(2)
	v_mfma_f32_32x32x16_bf16 v[34:49], v[242:245], v[70:73], v[34:49]
	s_waitcnt lgkmcnt(1)
	v_mfma_f32_32x32x16_bf16 v[34:49], v[246:249], v[74:77], v[34:49]
	s_waitcnt lgkmcnt(0)
	v_mfma_f32_32x32x16_bf16 v[34:49], v[250:253], v[78:81], v[34:49]
	v_cvt_f32_u32_e32 v0, v190
	v_cmp_gt_u32_e32 vcc, s88, v190
	s_and_b64 vcc, s[10:11], vcc
	s_nop 4
	v_fma_f32 v0, -v118, v0, v50
	s_nop 1
	v_cndmask_b32_e32 v98, v144, v0, vcc
	v_add_u32_e32 v0, -1, v190
	v_cvt_f32_u32_e32 v0, v0
	v_cmp_lt_i32_e32 vcc, 0, v190
	s_and_b64 vcc, s[10:11], vcc
	v_fma_f32 v0, -v118, v0, v51
	v_add_u32_e32 v51, -2, v190
	v_cndmask_b32_e32 v50, v144, v0, vcc
	v_cmp_gt_u32_e32 vcc, s88, v51
	v_cvt_f32_u32_e32 v51, v51
	s_and_b64 vcc, s[10:11], vcc
	v_max3_f32 v0, v98, s28, v50
	v_fma_f32 v51, -v118, v51, v52
	v_cndmask_b32_e32 v52, v144, v51, vcc
	v_add_u32_e32 v51, -3, v190
	v_cmp_gt_u32_e32 vcc, s88, v51
	v_cvt_f32_u32_e32 v51, v51
	s_and_b64 vcc, s[10:11], vcc
	v_fma_f32 v51, -v118, v51, v53
	v_add_u32_e32 v53, -4, v190
	v_cndmask_b32_e32 v51, v144, v51, vcc
	v_cmp_gt_u32_e32 vcc, s88, v53
	v_cvt_f32_u32_e32 v53, v53
	s_and_b64 vcc, s[10:11], vcc
	v_max3_f32 v0, v0, v52, v51
	v_fma_f32 v53, -v118, v53, v54
	v_add_u32_e32 v54, -5, v190
	v_cndmask_b32_e32 v53, v144, v53, vcc
	v_cmp_gt_u32_e32 vcc, s88, v54
	v_cvt_f32_u32_e32 v54, v54
	s_and_b64 vcc, s[10:11], vcc
	v_fma_f32 v54, -v118, v54, v55
	v_add_u32_e32 v55, -6, v190
	v_cndmask_b32_e32 v54, v144, v54, vcc
	v_cmp_gt_u32_e32 vcc, s88, v55
	v_cvt_f32_u32_e32 v55, v55
	s_and_b64 vcc, s[10:11], vcc
	v_max3_f32 v0, v0, v53, v54
	v_fma_f32 v55, -v118, v55, v56
	v_add_u32_e32 v56, -7, v190
	v_cndmask_b32_e32 v55, v144, v55, vcc
	v_cmp_gt_u32_e32 vcc, s88, v56
	v_cvt_f32_u32_e32 v56, v56
	s_and_b64 vcc, s[10:11], vcc
	v_fma_f32 v56, -v118, v56, v57
	v_add_u32_e32 v57, -16, v190
	v_cndmask_b32_e32 v56, v144, v56, vcc
	v_cmp_gt_u32_e32 vcc, s88, v57
	v_cvt_f32_u32_e32 v57, v57
	s_and_b64 vcc, s[10:11], vcc
	v_max3_f32 v0, v0, v55, v56
	v_fma_f32 v57, -v118, v57, v58
	v_subrev_u32_e32 v58, 17, v190
	v_cndmask_b32_e32 v57, v144, v57, vcc
	v_cmp_gt_u32_e32 vcc, s88, v58
	v_cvt_f32_u32_e32 v58, v58
	s_and_b64 vcc, s[10:11], vcc
	v_fma_f32 v58, -v118, v58, v59
	v_subrev_u32_e32 v59, 18, v190
	v_cndmask_b32_e32 v58, v144, v58, vcc
	v_cmp_gt_u32_e32 vcc, s88, v59
	v_cvt_f32_u32_e32 v59, v59
	s_and_b64 vcc, s[10:11], vcc
	v_max3_f32 v0, v0, v57, v58
	v_fma_f32 v59, -v118, v59, v60
	v_subrev_u32_e32 v60, 19, v190
	v_cndmask_b32_e32 v59, v144, v59, vcc
	v_cmp_gt_u32_e32 vcc, s88, v60
	v_cvt_f32_u32_e32 v60, v60
	s_and_b64 vcc, s[10:11], vcc
	v_fma_f32 v60, -v118, v60, v61
	v_subrev_u32_e32 v61, 20, v190
	v_cndmask_b32_e32 v60, v144, v60, vcc
	v_cmp_gt_u32_e32 vcc, s88, v61
	v_cvt_f32_u32_e32 v61, v61
	s_and_b64 vcc, s[10:11], vcc
	v_max3_f32 v0, v0, v59, v60
	v_fma_f32 v61, -v118, v61, v62
	v_subrev_u32_e32 v62, 21, v190
	v_cndmask_b32_e32 v61, v144, v61, vcc
	v_cmp_gt_u32_e32 vcc, s88, v62
	v_cvt_f32_u32_e32 v62, v62
	s_and_b64 vcc, s[10:11], vcc
	v_fma_f32 v62, -v118, v62, v63
	v_subrev_u32_e32 v63, 22, v190
	v_cndmask_b32_e32 v62, v144, v62, vcc
	v_cmp_gt_u32_e32 vcc, s88, v63
	v_cvt_f32_u32_e32 v63, v63
	s_and_b64 vcc, s[10:11], vcc
	v_max3_f32 v0, v0, v61, v62
	v_fma_f32 v63, -v118, v63, v64
	v_subrev_u32_e32 v64, 23, v190
	v_cndmask_b32_e32 v63, v144, v63, vcc
	v_cmp_gt_u32_e32 vcc, s88, v64
	v_cvt_f32_u32_e32 v64, v64
	s_and_b64 vcc, s[10:11], vcc
	v_fma_f32 v64, -v118, v64, v65
	v_subrev_u32_e32 v65, 32, v190
	v_cndmask_b32_e32 v64, v144, v64, vcc
	v_cmp_gt_u32_e32 vcc, s88, v65
	v_cvt_f32_u32_e32 v65, v65
	s_and_b64 vcc, s[10:11], vcc
	v_max3_f32 v0, v0, v63, v64
	v_fma_f32 v34, -v118, v65, v34
	v_subrev_u32_e32 v65, 33, v190
	v_cndmask_b32_e32 v34, v144, v34, vcc
	v_cmp_gt_u32_e32 vcc, s88, v65
	v_cvt_f32_u32_e32 v65, v65
	s_and_b64 vcc, s[10:11], vcc
	v_fma_f32 v35, -v118, v65, v35
	v_subrev_u32_e32 v65, 34, v190
	v_cndmask_b32_e32 v35, v144, v35, vcc
	v_cmp_gt_u32_e32 vcc, s88, v65
	v_cvt_f32_u32_e32 v65, v65
	s_and_b64 vcc, s[10:11], vcc
	v_max3_f32 v0, v0, v34, v35
	v_fma_f32 v36, -v118, v65, v36
	v_subrev_u32_e32 v65, 35, v190
	v_cndmask_b32_e32 v36, v144, v36, vcc
	v_cmp_gt_u32_e32 vcc, s88, v65
	v_cvt_f32_u32_e32 v65, v65
	s_and_b64 vcc, s[10:11], vcc
	v_fma_f32 v37, -v118, v65, v37
	v_subrev_u32_e32 v65, 36, v190
	v_cndmask_b32_e32 v37, v144, v37, vcc
	v_cmp_gt_u32_e32 vcc, s88, v65
	v_cvt_f32_u32_e32 v65, v65
	s_and_b64 vcc, s[10:11], vcc
	v_max3_f32 v0, v0, v36, v37
	v_fma_f32 v38, -v118, v65, v38
	v_subrev_u32_e32 v65, 37, v190
	v_cndmask_b32_e32 v38, v144, v38, vcc
	v_cmp_gt_u32_e32 vcc, s88, v65
	v_cvt_f32_u32_e32 v65, v65
	s_and_b64 vcc, s[10:11], vcc
	v_fma_f32 v39, -v118, v65, v39
	v_subrev_u32_e32 v65, 38, v190
	v_cndmask_b32_e32 v39, v144, v39, vcc
	v_cmp_gt_u32_e32 vcc, s88, v65
	v_cvt_f32_u32_e32 v65, v65
	s_and_b64 vcc, s[10:11], vcc
	v_max3_f32 v0, v0, v38, v39
	v_fma_f32 v40, -v118, v65, v40
	v_subrev_u32_e32 v65, 39, v190
	v_cndmask_b32_e32 v40, v144, v40, vcc
	v_cmp_gt_u32_e32 vcc, s88, v65
	v_cvt_f32_u32_e32 v65, v65
	s_and_b64 vcc, s[10:11], vcc
	v_fma_f32 v41, -v118, v65, v41
	v_subrev_u32_e32 v65, 48, v190
	v_cndmask_b32_e32 v41, v144, v41, vcc
	v_cmp_gt_u32_e32 vcc, s88, v65
	v_cvt_f32_u32_e32 v65, v65
	s_and_b64 vcc, s[10:11], vcc
	v_max3_f32 v0, v0, v40, v41
	v_fma_f32 v42, -v118, v65, v42
	v_subrev_u32_e32 v65, 49, v190
	v_cndmask_b32_e32 v42, v144, v42, vcc
	v_cmp_gt_u32_e32 vcc, s88, v65
	v_cvt_f32_u32_e32 v65, v65
	s_and_b64 vcc, s[10:11], vcc
	v_fma_f32 v43, -v118, v65, v43
	v_subrev_u32_e32 v65, 50, v190
	v_cndmask_b32_e32 v43, v144, v43, vcc
	v_cmp_gt_u32_e32 vcc, s88, v65
	v_cvt_f32_u32_e32 v65, v65
	s_and_b64 vcc, s[10:11], vcc
	v_max3_f32 v0, v0, v42, v43
	v_fma_f32 v44, -v118, v65, v44
	v_subrev_u32_e32 v65, 51, v190
	v_cndmask_b32_e32 v44, v144, v44, vcc
	v_cmp_gt_u32_e32 vcc, s88, v65
	v_cvt_f32_u32_e32 v65, v65
	s_and_b64 vcc, s[10:11], vcc
	v_fma_f32 v45, -v118, v65, v45
	v_subrev_u32_e32 v65, 52, v190
	v_cndmask_b32_e32 v45, v144, v45, vcc
	v_cmp_gt_u32_e32 vcc, s88, v65
	v_cvt_f32_u32_e32 v65, v65
	s_and_b64 vcc, s[10:11], vcc
	v_max3_f32 v0, v0, v44, v45
	v_fma_f32 v46, -v118, v65, v46
	v_subrev_u32_e32 v65, 53, v190
	v_cndmask_b32_e32 v46, v144, v46, vcc
	v_cmp_gt_u32_e32 vcc, s88, v65
	v_cvt_f32_u32_e32 v65, v65
	s_and_b64 vcc, s[10:11], vcc
	v_fma_f32 v47, -v118, v65, v47
	v_subrev_u32_e32 v65, 54, v190
	v_cndmask_b32_e32 v47, v144, v47, vcc
	v_cmp_gt_u32_e32 vcc, s88, v65
	v_cvt_f32_u32_e32 v65, v65
	s_and_b64 vcc, s[10:11], vcc
	v_max3_f32 v0, v0, v46, v47
	v_fma_f32 v48, -v118, v65, v48
	v_cndmask_b32_e32 v65, v144, v48, vcc
	v_subrev_u32_e32 v48, 55, v190
	v_cmp_gt_u32_e32 vcc, s88, v48
	v_cvt_f32_u32_e32 v48, v48
	s_and_b64 vcc, s[10:11], vcc
	v_fma_f32 v48, -v118, v48, v49
	v_cndmask_b32_e32 v99, v144, v48, vcc
	v_max3_f32 v0, v0, v65, v99
	ds_bpermute_b32 v48, v186, v0
	s_waitcnt lgkmcnt(0)
	v_max3_f32 v0, v189, v0, v48
	v_cmp_gt_f32_e32 vcc, v0, v189
	s_cbranch_vccz .LBB0_886
	v_sub_f32_e32 v48, v189, v0
	v_exp_f32_e32 v48, v48
	s_nop 0
	v_mul_f32_e32 v188, v188, v48
	v_pk_mul_f32 v[32:33], v[32:33], v[48:49] op_sel_hi:[1,0]
	v_pk_mul_f32 v[30:31], v[30:31], v[48:49] op_sel_hi:[1,0]
	v_pk_mul_f32 v[28:29], v[28:29], v[48:49] op_sel_hi:[1,0]
	v_pk_mul_f32 v[26:27], v[26:27], v[48:49] op_sel_hi:[1,0]
	v_pk_mul_f32 v[24:25], v[24:25], v[48:49] op_sel_hi:[1,0]
	v_pk_mul_f32 v[22:23], v[22:23], v[48:49] op_sel_hi:[1,0]
	v_pk_mul_f32 v[20:21], v[20:21], v[48:49] op_sel_hi:[1,0]
	v_pk_mul_f32 v[18:19], v[18:19], v[48:49] op_sel_hi:[1,0]
	v_pk_mul_f32 v[16:17], v[16:17], v[48:49] op_sel_hi:[1,0]
	v_pk_mul_f32 v[14:15], v[14:15], v[48:49] op_sel_hi:[1,0]
	v_pk_mul_f32 v[12:13], v[12:13], v[48:49] op_sel_hi:[1,0]
	v_pk_mul_f32 v[10:11], v[10:11], v[48:49] op_sel_hi:[1,0]
	v_pk_mul_f32 v[8:9], v[8:9], v[48:49] op_sel_hi:[1,0]
	v_pk_mul_f32 v[6:7], v[6:7], v[48:49] op_sel_hi:[1,0]
	v_pk_mul_f32 v[4:5], v[4:5], v[48:49] op_sel_hi:[1,0]
	v_pk_mul_f32 v[2:3], v[2:3], v[48:49] op_sel_hi:[1,0]
